# v54 with P1/P8 copier quotas 22 -> 20 (epilogues are shorter now, copiers were the last to arrive)
# baseline (speedup 1.0000x reference)
; #define LAS __attribute__((address_space(3)))
; __device__ __forceinline__ void copy_quota(const Args& a, unsigned* ctl, int quota, volatile LAS unsigned* misc, int tid) {
;     for (int k = 0; k < quota; ++k) {
;         if (tid == 0) misc[24 + (k & 1)] = __hip_atomic_fetch_add(ctl, 1u, __ATOMIC_RELAXED, __HIP_MEMORY_SCOPE_AGENT);
;         __syncthreads();
;         const unsigned id = (unsigned)__builtin_amdgcn_readfirstlane((int)misc[24 + (k & 1)]);
;         if (id >= (unsigned)N_CHUNKS) break;
;         copy_chunk(a, (int)id, tid);
;     }
.LBB0_152:
	s_or_b64 exec, exec, s[8:9]
	s_add_i32 s49, s49, 1
	s_cmp_eq_u32 s49, 20
	s_cselect_b64 s[8:9], -1, 0

; #define LAS __attribute__((address_space(3)))
; __device__ __forceinline__ void copy_quota(const Args& a, unsigned* ctl, int quota, volatile LAS unsigned* misc, int tid) {
;     for (int k = 0; k < quota; ++k) {
;         if (tid == 0) misc[24 + (k & 1)] = __hip_atomic_fetch_add(ctl, 1u, __ATOMIC_RELAXED, __HIP_MEMORY_SCOPE_AGENT);
;         __syncthreads();
;         const unsigned id = (unsigned)__builtin_amdgcn_readfirstlane((int)misc[24 + (k & 1)]);
;         if (id >= (unsigned)N_CHUNKS) break;
;         copy_chunk(a, (int)id, tid);
;     }
.LBB0_1496:
	s_add_i32 s33, s68, -8
	s_cmp_ge_i32 s96, s33
	s_cselect_b64 s[2:3], -1, 0
	s_cbranch_scc1 .Lp8_chain
	s_add_i32 s98, s68, -48
	s_cmp_lt_i32 s96, s98
	s_cbranch_scc1 .LBB0_1560
	s_movk_i32 s99, 20
	s_load_dwordx8 s[16:23], s[90:91], 0x10
	s_load_dwordx4 s[24:27], s[90:91], 0x30
	s_load_dwordx2 s[28:29], s[90:91], 0x40
	s_load_dwordx2 s[30:31], s[90:91], 0xd8
	s_add_u32 s14, s80, 0x4000
	s_addc_u32 s15, s81, 0
	v_and_b32_e32 v66, 63, v0
	v_lshlrev_b32_e32 v66, 4, v66
	v_readfirstlane_b32 s34, v0
	s_lshr_b32 s34, s34, 6
	s_lshl_b32 s34, s34, 10
	v_cmp_eq_u32_e32 vcc, 0, v0
	s_and_saveexec_b64 s[46:47], vcc
	s_cbranch_execz .Lfc8_noatom
	v_mov_b32_e32 v67, 0
	v_mov_b32_e32 v68, s99
	global_atomic_add v68, v67, v68, s[14:15] sc0
	v_mov_b32_e32 v67, 0x20070
	s_waitcnt vmcnt(0)
	ds_write_b32 v67, v68
